# attention: one static s_setprio 1 for waves 4-7 before the unit loop, reset at phase exit
# speedup vs baseline: 1.0033x; 1.0033x over previous
.LBB0_383:
	s_add_u32 s4, s58, 0x100000
	s_addc_u32 s5, s59, 0
	v_writelane_b32 v255, s4, 22
	v_and_b32_e32 v0, 63, v6
	s_nop 0
	v_writelane_b32 v255, s5, 23
	s_nop 0
	v_readlane_b32 s4, v255, 16
	v_readlane_b32 s5, v255, 17
	s_and_b64 vcc, exec, s[4:5]
	s_cbranch_vccnz .LBB0_429
	v_mov_b32_e32 v88, 0
	v_and_b32_e32 v2, 0x70, v8
	v_mov_b32_e32 v3, v88
	v_add_u32_e32 v1, 0, v2
	v_lshl_add_u64 v[136:137], s[42:43], 0, v[2:3]
	v_add_u32_e32 v2, 0x200, v6
	v_ashrrev_i32_e32 v177, 3, v2
	v_add_u32_e32 v2, 0x400, v6
	v_ashrrev_i32_e32 v179, 3, v2
	v_add_u32_e32 v2, 0x600, v6
	s_ashr_i32 s4, s35, 7
	v_ashrrev_i32_e32 v181, 3, v2
	v_add_u32_e32 v2, 0x800, v6
	v_writelane_b32 v255, s4, 24
	v_ashrrev_i32_e32 v183, 3, v2
	v_add_u32_e32 v2, 0xa00, v6
	v_cmp_gt_u32_e64 s[4:5], 32, v0
	v_and_b32_e32 v0, 3, v6
	v_ashrrev_i32_e32 v185, 3, v2
	v_lshlrev_b32_e32 v4, 1, v6
	v_lshrrev_b32_e32 v2, 1, v6
	s_movk_i32 s83, 0x90
	v_lshlrev_b32_e32 v0, 3, v0
	s_lshl_b32 s81, s34, 5
	v_lshlrev_b32_e32 v134, 3, v7
	v_and_b32_e32 v3, 19, v6
	v_and_b32_e32 v5, 8, v4
	v_and_b32_e32 v8, 4, v2
	v_lshrrev_b32_e32 v9, 2, v6
	v_lshlrev_b32_e32 v2, 2, v7
	v_mul_lo_u32 v7, v176, s83
	v_mul_lo_u32 v10, v177, s83
	v_mul_lo_u32 v11, v179, s83
	v_mul_lo_u32 v12, v181, s83
	v_mul_lo_u32 v13, v183, s83
	v_mul_lo_u32 v14, v185, s83
	v_and_or_b32 v138, v4, 32, v0
	s_mov_b32 s34, 0x41a00000
	s_mov_b32 s36, 2.0
	s_mov_b32 s60, 4.0
	s_mov_b32 s62, 0x40c00000
	s_mov_b32 s64, 0x41800000
	s_mov_b32 s70, 0x41900000
	s_mov_b32 s72, 0x41b00000
	v_mbcnt_lo_u32_b32 v0, -1, 0
	s_mov_b32 s15, 0
	s_and_b32 s82, s81, 32
	v_add_u32_e32 v133, 0xffffff80, v176
	v_add_u32_e32 v178, 0xffffff80, v177
	v_add_u32_e32 v180, 0xffffff80, v179
	v_add_u32_e32 v182, 0xffffff80, v181
	v_add_u32_e32 v184, 0xffffff80, v183
	v_add_u32_e32 v186, 0xffffff80, v185
	v_cndmask_b32_e64 v187, 0, 1.0, s[4:5]
	v_sub_u32_e32 v188, v139, v134
	v_and_or_b32 v189, v9, 3, v134
	v_or3_b32 v190, v3, v5, v8
	v_add_u32_e32 v191, v1, v7
	v_add_u32_e32 v192, v1, v10
	v_add_u32_e32 v193, v1, v11
	v_add_u32_e32 v194, v1, v12
	v_add_u32_e32 v195, v1, v13
	v_add_u32_e32 v196, v1, v14
	s_movk_i32 s84, 0x1800
	s_mov_b32 s35, 0x41a80000
	s_mov_b32 s37, 0x40400000
	s_mov_b32 s61, 0x40a00000
	s_mov_b32 s63, 0x40e00000
	s_mov_b32 s65, 0x41880000
	s_mov_b32 s71, 0x41980000
	s_mov_b32 s73, 0x41b80000
	s_mov_b32 s85, 0xff800000
	v_lshlrev_b32_e32 v140, 1, v2
	v_mov_b32_e32 v197, 0x3fb8aa3b
	v_mov_b32_e32 v198, 0x42800000
	v_mbcnt_hi_u32_b32 v199, -1, v0
	v_mov_b32_e32 v200, 0xff800000
	s_mov_b32 s86, s2
	s_waitcnt vmcnt(0)
	v_readfirstlane_b32 s98, v254
	s_nop 3
	s_lshr_b32 s98, s98, 6
	s_cmp_ge_u32 s98, 4
	s_cbranch_scc0 .Lsp3
	s_setprio 1
.Lsp3:
	s_branch .LBB0_386

.LBB0_429:
	s_setprio 0
	s_waitcnt vmcnt(0)
	s_barrier
	s_mov_b64 s[0:1], exec
	v_readlane_b32 s4, v255, 7
	v_readlane_b32 s5, v255, 8
	s_and_b64 s[4:5], s[0:1], s[4:5]
	v_readlane_b32 s64, v255, 9
	v_readlane_b32 s65, v255, 10
	s_mov_b64 exec, s[4:5]
	s_cbranch_execz .LBB0_481
	s_add_i32 s4, 0, 0x20160
	v_mov_b32_e32 v0, s4
	s_waitcnt vmcnt(0) expcnt(0) lgkmcnt(0)
	ds_read_b32 v2, v0
	s_add_i32 s4, 0, 0x20164
	v_mov_b32_e32 v0, s4
	ds_read_b32 v0, v0
	s_waitcnt lgkmcnt(1)
	v_cmp_ne_u32_e32 vcc, 0, v2
	s_cbranch_vccnz .LBB0_445
	v_readlane_b32 s4, v255, 1
	v_readlane_b32 s5, v255, 2
	s_load_dword s4, s[4:5], 0x14
	s_mov_b32 s82, 1
	v_mov_b32_e32 v16, 0
	s_waitcnt lgkmcnt(0)
	s_lshr_b32 s6, s4, 16
	s_and_b32 s4, s4, 0xffff
	s_cmp_lg_u32 s4, 0
	s_cselect_b64 s[4:5], -1, 0
	s_cmp_lg_u64 s[4:5], 0
	s_addc_u32 s4, s39, 0
	s_cmp_lg_u32 s6, 0
	s_mul_i32 s83, s4, s38
	s_cselect_b64 s[4:5], -1, 0
	s_cmp_lg_u64 s[4:5], 0
	v_readlane_b32 s4, v255, 0
	s_addc_u32 s4, s4, 0
	s_mul_i32 s83, s83, s4
	s_add_u32 s4, s58, 0x80200
	s_addc_u32 s5, s59, 0
	s_add_u32 s6, s58, 0x80400
	s_addc_u32 s7, s59, 0
	s_add_u32 s8, s58, 0x80500
	s_addc_u32 s9, s59, 0
	s_add_u32 s10, s58, 0x80600
	s_addc_u32 s11, s59, 0
	s_add_u32 s12, s58, 0x80700
	s_addc_u32 s13, s59, 0
	s_add_u32 s14, s58, 0x80800
	s_addc_u32 s15, s59, 0
	s_add_u32 s34, s58, 0x80900
	s_addc_u32 s35, s59, 0
	s_add_u32 s36, s58, 0x80a00
	s_addc_u32 s37, s59, 0
	s_add_u32 s46, s58, 0x80b00
	s_addc_u32 s47, s59, 0
	s_add_u32 s60, s58, 0x80c00
	s_addc_u32 s61, s59, 0
	s_add_u32 s62, s58, 0x80d00
	s_addc_u32 s63, s59, 0
	s_add_u32 s64, s58, 0x80e00
	s_addc_u32 s65, s59, 0
	s_add_u32 s70, s58, 0x80f00
	s_addc_u32 s71, s59, 0
	s_add_u32 s72, s58, 0x81000
	s_addc_u32 s73, s59, 0
	s_add_u32 s74, s58, 0x81100
	s_addc_u32 s75, s59, 0
	s_add_u32 s76, s58, 0x81200
	s_addc_u32 s77, s59, 0
	s_add_u32 s78, s58, 0x81300
	s_addc_u32 s79, s59, 0
	s_branch .LBB0_433

.LBB0_1243:
	v_readlane_b32 s8, v255, 16
	v_readlane_b32 s9, v255, 17
	v_and_b32_e32 v0, 63, v6
	s_and_b64 vcc, exec, s[8:9]
	s_cbranch_vccnz .LBB0_1289
	v_mov_b32_e32 v88, 0
	v_and_b32_e32 v2, 0x70, v8
	v_mov_b32_e32 v3, v88
	v_add_u32_e32 v1, 0, v2
	v_lshl_add_u64 v[136:137], s[42:43], 0, v[2:3]
	v_add_u32_e32 v2, 0x200, v6
	v_ashrrev_i32_e32 v177, 3, v2
	v_add_u32_e32 v2, 0x400, v6
	v_ashrrev_i32_e32 v179, 3, v2
	v_add_u32_e32 v2, 0x600, v6
	v_ashrrev_i32_e32 v181, 3, v2
	v_add_u32_e32 v2, 0x800, v6
	s_ashr_i32 s5, s35, 7
	v_ashrrev_i32_e32 v183, 3, v2
	v_add_u32_e32 v2, 0xa00, v6
	v_cmp_gt_u32_e64 s[8:9], 32, v0
	v_and_b32_e32 v0, 3, v6
	v_writelane_b32 v255, s5, 50
	s_lshl_b32 s5, s34, 5
	v_ashrrev_i32_e32 v185, 3, v2
	v_lshlrev_b32_e32 v4, 1, v6
	v_lshrrev_b32_e32 v2, 1, v6
	s_movk_i32 s71, 0x90
	v_lshlrev_b32_e32 v0, 3, v0
	v_writelane_b32 v255, s5, 52
	s_and_b32 s5, s5, 32
	v_lshlrev_b32_e32 v134, 3, v7
	v_and_b32_e32 v3, 19, v6
	v_and_b32_e32 v5, 8, v4
	v_and_b32_e32 v8, 4, v2
	v_lshrrev_b32_e32 v9, 2, v6
	v_lshlrev_b32_e32 v2, 2, v7
	v_mul_lo_u32 v7, v176, s71
	v_mul_lo_u32 v10, v177, s71
	v_mul_lo_u32 v11, v179, s71
	v_mul_lo_u32 v12, v181, s71
	v_mul_lo_u32 v13, v183, s71
	v_mul_lo_u32 v14, v185, s71
	v_and_or_b32 v138, v4, 32, v0
	s_mov_b32 s34, 0x41a00000
	s_mov_b32 s36, 2.0
	s_mov_b32 s60, 4.0
	s_mov_b32 s82, 0x40c00000
	s_mov_b32 s88, 0x41800000
	s_mov_b32 s92, 0x41900000
	s_mov_b32 s94, 0x41b00000
	v_mbcnt_lo_u32_b32 v0, -1, 0
	s_mov_b32 s15, 0
	v_writelane_b32 v255, s5, 53
	v_add_u32_e32 v133, 0xffffff80, v176
	v_add_u32_e32 v178, 0xffffff80, v177
	v_add_u32_e32 v180, 0xffffff80, v179
	v_add_u32_e32 v182, 0xffffff80, v181
	v_add_u32_e32 v184, 0xffffff80, v183
	v_add_u32_e32 v186, 0xffffff80, v185
	v_cndmask_b32_e64 v187, 0, 1.0, s[8:9]
	v_sub_u32_e32 v188, v139, v134
	v_and_or_b32 v189, v9, 3, v134
	v_or3_b32 v190, v3, v5, v8
	v_add_u32_e32 v191, v1, v7
	v_add_u32_e32 v192, v1, v10
	v_add_u32_e32 v193, v1, v11
	v_add_u32_e32 v194, v1, v12
	v_add_u32_e32 v195, v1, v13
	v_add_u32_e32 v196, v1, v14
	s_movk_i32 s72, 0x1800
	s_mov_b32 s35, 0x41a80000
	s_mov_b32 s37, 0x40400000
	s_mov_b32 s61, 0x40a00000
	s_mov_b32 s83, 0x40e00000
	s_mov_b32 s89, 0x41880000
	s_mov_b32 s93, 0x41980000
	s_mov_b32 s95, 0x41b80000
	s_mov_b32 s73, 0xff800000
	v_lshlrev_b32_e32 v140, 1, v2
	v_mov_b32_e32 v197, 0x3fb8aa3b
	v_mov_b32_e32 v198, 0x42800000
	v_mbcnt_hi_u32_b32 v199, -1, v0
	v_mov_b32_e32 v200, 0xff800000
	s_mov_b32 s78, s2
	s_waitcnt vmcnt(0)
	v_readfirstlane_b32 s98, v254
	s_nop 3
	s_lshr_b32 s98, s98, 6
	s_cmp_ge_u32 s98, 4
	s_cbranch_scc0 .Lsp11
	s_setprio 1

.LBB0_1289:
	s_setprio 0
	s_waitcnt vmcnt(0)
	s_barrier
	s_mov_b64 s[0:1], exec
	v_readlane_b32 s4, v255, 7
	v_readlane_b32 s5, v255, 8
	s_and_b64 s[4:5], s[0:1], s[4:5]
	v_readlane_b32 s64, v255, 9
	v_readlane_b32 s65, v255, 10
	s_mov_b64 exec, s[4:5]
	s_cbranch_execz .LBB0_1341
	s_add_i32 s4, 0, 0x20160
	v_mov_b32_e32 v0, s4
	s_waitcnt vmcnt(0) expcnt(0) lgkmcnt(0)
	ds_read_b32 v2, v0
	s_add_i32 s4, 0, 0x20164
	v_mov_b32_e32 v0, s4
	ds_read_b32 v0, v0
	s_waitcnt lgkmcnt(1)
	v_cmp_ne_u32_e32 vcc, 0, v2
	s_cbranch_vccnz .LBB0_1305
	v_readlane_b32 s4, v255, 1
	v_readlane_b32 s5, v255, 2
	s_load_dword s4, s[4:5], 0x14
	s_mov_b32 s64, 1
	v_mov_b32_e32 v16, 0
	s_waitcnt lgkmcnt(0)
	s_lshr_b32 s6, s4, 16
	s_and_b32 s4, s4, 0xffff
	s_cmp_lg_u32 s4, 0
	s_cselect_b64 s[4:5], -1, 0
	s_cmp_lg_u64 s[4:5], 0
	s_addc_u32 s4, s39, 0
	s_cmp_lg_u32 s6, 0
	s_mul_i32 s65, s4, s38
	s_cselect_b64 s[4:5], -1, 0
	s_cmp_lg_u64 s[4:5], 0
	v_readlane_b32 s4, v255, 0
	s_addc_u32 s4, s4, 0
	s_mul_i32 s65, s65, s4
	s_add_u32 s4, s58, 0x80200
	s_addc_u32 s5, s59, 0
	s_add_u32 s6, s58, 0x80400
	s_addc_u32 s7, s59, 0
	s_add_u32 s8, s58, 0x80500
	s_addc_u32 s9, s59, 0
	s_add_u32 s10, s58, 0x80600
	s_addc_u32 s11, s59, 0
	s_add_u32 s12, s58, 0x80700
	s_addc_u32 s13, s59, 0
	s_add_u32 s14, s58, 0x80800
	s_addc_u32 s15, s59, 0
	s_add_u32 s34, s58, 0x80900
	s_addc_u32 s35, s59, 0
	s_add_u32 s36, s58, 0x80a00
	s_addc_u32 s37, s59, 0
	s_add_u32 s40, s58, 0x80b00
	s_addc_u32 s41, s59, 0
	s_add_u32 s46, s58, 0x80c00
	s_addc_u32 s47, s59, 0
	s_add_u32 s60, s58, 0x80d00
	s_addc_u32 s61, s59, 0
	s_add_u32 s74, s58, 0x80e00
	s_addc_u32 s75, s59, 0
	s_add_u32 s82, s58, 0x80f00
	s_addc_u32 s83, s59, 0
	s_add_u32 s88, s58, 0x81000
	s_addc_u32 s89, s59, 0
	s_add_u32 s92, s58, 0x81100
	s_addc_u32 s93, s59, 0
	s_add_u32 s94, s58, 0x81200
	s_addc_u32 s95, s59, 0
	s_add_u32 s96, s58, 0x81300
	s_addc_u32 s97, s59, 0
	s_branch .LBB0_1293

.LBB0_2103:
	v_readlane_b32 s8, v255, 16
	v_readlane_b32 s9, v255, 17
	v_and_b32_e32 v0, 63, v6
	s_and_b64 vcc, exec, s[8:9]
	s_cbranch_vccnz .LBB0_2150
	v_mov_b32_e32 v88, 0
	v_and_b32_e32 v2, 0x70, v8
	v_mov_b32_e32 v3, v88
	v_add_u32_e32 v1, 0, v2
	v_lshl_add_u64 v[136:137], s[42:43], 0, v[2:3]
	v_add_u32_e32 v2, 0x200, v6
	v_ashrrev_i32_e32 v177, 3, v2
	v_add_u32_e32 v2, 0x400, v6
	v_ashrrev_i32_e32 v179, 3, v2
	v_add_u32_e32 v2, 0x600, v6
	v_ashrrev_i32_e32 v181, 3, v2
	v_add_u32_e32 v2, 0x800, v6
	v_ashrrev_i32_e32 v183, 3, v2
	v_add_u32_e32 v2, 0xa00, v6
	v_cmp_gt_u32_e64 s[10:11], 32, v0
	v_and_b32_e32 v0, 3, v6
	s_ashr_i32 s5, s35, 7
	s_lshl_b32 s69, s34, 5
	v_ashrrev_i32_e32 v185, 3, v2
	v_lshlrev_b32_e32 v4, 1, v6
	v_lshrrev_b32_e32 v2, 1, v6
	s_movk_i32 s71, 0x90
	v_lshlrev_b32_e32 v0, 3, v0
	v_writelane_b32 v255, s5, 52
	s_and_b32 s5, s69, 32
	v_lshlrev_b32_e32 v134, 3, v7
	v_and_b32_e32 v3, 19, v6
	v_and_b32_e32 v5, 8, v4
	v_and_b32_e32 v8, 4, v2
	v_lshrrev_b32_e32 v9, 2, v6
	v_lshlrev_b32_e32 v2, 2, v7
	v_mul_lo_u32 v7, v176, s71
	v_mul_lo_u32 v10, v177, s71
	v_mul_lo_u32 v11, v179, s71
	v_mul_lo_u32 v12, v181, s71
	v_mul_lo_u32 v13, v183, s71
	v_mul_lo_u32 v14, v185, s71
	v_and_or_b32 v138, v4, 32, v0
	s_mov_b32 s34, 0x41a00000
	s_mov_b32 s36, 2.0
	s_mov_b32 s60, 4.0
	s_mov_b32 s82, 0x40c00000
	s_mov_b32 s88, 0x41800000
	s_mov_b32 s94, 0x41900000
	s_mov_b32 s96, 0x41b00000
	v_mbcnt_lo_u32_b32 v0, -1, 0
	s_mov_b32 s9, 0
	v_writelane_b32 v255, s5, 53
	v_add_u32_e32 v133, 0xffffff80, v176
	v_add_u32_e32 v178, 0xffffff80, v177
	v_add_u32_e32 v180, 0xffffff80, v179
	v_add_u32_e32 v182, 0xffffff80, v181
	v_add_u32_e32 v184, 0xffffff80, v183
	v_add_u32_e32 v186, 0xffffff80, v185
	v_cndmask_b32_e64 v187, 0, 1.0, s[10:11]
	v_sub_u32_e32 v188, v139, v134
	v_and_or_b32 v189, v9, 3, v134
	v_or3_b32 v190, v3, v5, v8
	v_add_u32_e32 v191, v1, v7
	v_add_u32_e32 v192, v1, v10
	v_add_u32_e32 v193, v1, v11
	v_add_u32_e32 v194, v1, v12
	v_add_u32_e32 v195, v1, v13
	v_add_u32_e32 v196, v1, v14
	s_movk_i32 s72, 0x1800
	s_mov_b32 s35, 0x41a80000
	s_mov_b32 s37, 0x40400000
	s_mov_b32 s61, 0x40a00000
	s_mov_b32 s83, 0x40e00000
	s_mov_b32 s89, 0x41880000
	s_mov_b32 s95, 0x41980000
	s_mov_b32 s97, 0x41b80000
	s_mov_b32 s73, 0xff800000
	v_lshlrev_b32_e32 v140, 1, v2
	v_mov_b32_e32 v197, 0x3fb8aa3b
	v_mov_b32_e32 v198, 0x42800000
	v_mbcnt_hi_u32_b32 v199, -1, v0
	v_mov_b32_e32 v200, 0xff800000
	s_mov_b32 s78, s2
	s_waitcnt vmcnt(0)
	v_readfirstlane_b32 s98, v254
	s_nop 3
	s_lshr_b32 s98, s98, 6
	s_cmp_ge_u32 s98, 4
	s_cbranch_scc0 .Lsp19
	s_setprio 1

.LBB0_2149:
	s_setprio 0
	v_readlane_b32 s72, v255, 50
	v_readlane_b32 s70, v255, 48
	v_readlane_b32 s73, v255, 51
	v_readlane_b32 s71, v255, 49

.LBB0_2967:
	v_readlane_b32 s6, v255, 16
	v_readlane_b32 s7, v255, 17
	v_and_b32_e32 v0, 63, v6
	s_and_b64 vcc, exec, s[6:7]
	s_cbranch_vccnz .LBB0_3013
	v_mov_b32_e32 v88, 0
	v_and_b32_e32 v2, 0x70, v8
	v_mov_b32_e32 v3, v88
	v_add_u32_e32 v1, 0, v2
	v_lshl_add_u64 v[136:137], s[42:43], 0, v[2:3]
	v_add_u32_e32 v2, 0x200, v6
	v_ashrrev_i32_e32 v177, 3, v2
	v_add_u32_e32 v2, 0x400, v6
	v_ashrrev_i32_e32 v179, 3, v2
	v_add_u32_e32 v2, 0x600, v6
	v_ashrrev_i32_e32 v181, 3, v2
	v_add_u32_e32 v2, 0x800, v6
	v_ashrrev_i32_e32 v183, 3, v2
	v_add_u32_e32 v2, 0xa00, v6
	v_cmp_gt_u32_e64 s[6:7], 32, v0
	v_and_b32_e32 v0, 3, v6
	v_ashrrev_i32_e32 v185, 3, v2
	v_lshlrev_b32_e32 v4, 1, v6
	v_lshrrev_b32_e32 v2, 1, v6
	s_movk_i32 s65, 0x90
	v_lshlrev_b32_e32 v0, 3, v0
	s_ashr_i32 s60, s19, 7
	s_lshl_b32 s61, s18, 5
	v_lshlrev_b32_e32 v134, 3, v7
	v_and_b32_e32 v3, 19, v6
	v_and_b32_e32 v5, 8, v4
	v_and_b32_e32 v8, 4, v2
	v_lshrrev_b32_e32 v9, 2, v6
	v_lshlrev_b32_e32 v2, 2, v7
	v_mul_lo_u32 v7, v176, s65
	v_mul_lo_u32 v10, v177, s65
	v_mul_lo_u32 v11, v179, s65
	v_mul_lo_u32 v12, v181, s65
	v_mul_lo_u32 v13, v183, s65
	v_mul_lo_u32 v14, v185, s65
	v_and_or_b32 v138, v4, 32, v0
	s_mov_b32 s18, 0x41a00000
	s_mov_b32 s22, 2.0
	s_mov_b32 s24, 4.0
	s_mov_b32 s26, 0x40c00000
	s_mov_b32 s34, 0x41800000
	s_mov_b32 s36, 0x41900000
	s_mov_b32 s48, 0x41b00000
	v_mbcnt_lo_u32_b32 v0, -1, 0
	s_mov_b32 s17, 0
	s_and_b32 s64, s61, 32
	v_add_u32_e32 v133, 0xffffff80, v176
	v_add_u32_e32 v178, 0xffffff80, v177
	v_add_u32_e32 v180, 0xffffff80, v179
	v_add_u32_e32 v182, 0xffffff80, v181
	v_add_u32_e32 v184, 0xffffff80, v183
	v_add_u32_e32 v186, 0xffffff80, v185
	v_cndmask_b32_e64 v187, 0, 1.0, s[6:7]
	v_sub_u32_e32 v188, v139, v134
	v_and_or_b32 v189, v9, 3, v134
	v_or3_b32 v190, v3, v5, v8
	v_add_u32_e32 v191, v1, v7
	v_add_u32_e32 v192, v1, v10
	v_add_u32_e32 v193, v1, v11
	v_add_u32_e32 v194, v1, v12
	v_add_u32_e32 v195, v1, v13
	v_add_u32_e32 v196, v1, v14
	s_movk_i32 s66, 0x1800
	s_mov_b32 s19, 0x41a80000
	s_mov_b32 s23, 0x40400000
	s_mov_b32 s25, 0x40a00000
	s_mov_b32 s27, 0x40e00000
	s_mov_b32 s35, 0x41880000
	s_mov_b32 s37, 0x41980000
	s_mov_b32 s49, 0x41b80000
	s_mov_b32 s67, 0xff800000
	v_lshlrev_b32_e32 v140, 1, v2
	v_mov_b32_e32 v197, 0x3fb8aa3b
	v_mov_b32_e32 v198, 0x42800000
	v_mbcnt_hi_u32_b32 v199, -1, v0
	v_mov_b32_e32 v200, 0xff800000
	s_mov_b32 s68, s2
	s_waitcnt vmcnt(0)
	v_readfirstlane_b32 s98, v254
	s_nop 3
	s_lshr_b32 s98, s98, 6
	s_cmp_ge_u32 s98, 4
	s_cbranch_scc0 .Lsp27
	s_setprio 1

.LBB0_3013:
	s_setprio 0
	s_waitcnt vmcnt(0)
	s_barrier
	s_mov_b64 s[0:1], exec
	v_readlane_b32 s4, v255, 7
	v_readlane_b32 s5, v255, 8
	s_and_b64 s[4:5], s[0:1], s[4:5]
	v_readlane_b32 s66, v255, 9
	v_readlane_b32 s67, v255, 10
	s_mov_b64 exec, s[4:5]
	s_cbranch_execz .LBB0_3066
	s_add_i32 s4, 0, 0x20160
	v_mov_b32_e32 v0, s4
	s_waitcnt vmcnt(0) expcnt(0) lgkmcnt(0)
	ds_read_b32 v2, v0
	s_add_i32 s4, 0, 0x20164
	v_mov_b32_e32 v0, s4
	ds_read_b32 v0, v0
	s_waitcnt lgkmcnt(1)
	v_cmp_ne_u32_e32 vcc, 0, v2
	s_cbranch_vccnz .LBB0_3030
	v_readlane_b32 s4, v255, 1
	v_readlane_b32 s5, v255, 2
	s_load_dword s4, s[4:5], 0x14
	s_mov_b32 s64, 1
	v_mov_b32_e32 v16, 0
	s_waitcnt lgkmcnt(0)
	s_lshr_b32 s6, s4, 16
	s_and_b32 s4, s4, 0xffff
	s_cmp_lg_u32 s4, 0
	s_cselect_b64 s[4:5], -1, 0
	s_cmp_lg_u64 s[4:5], 0
	s_addc_u32 s4, s39, 0
	s_cmp_lg_u32 s6, 0
	s_mul_i32 s65, s4, s38
	s_cselect_b64 s[4:5], -1, 0
	s_cmp_lg_u64 s[4:5], 0
	v_readlane_b32 s4, v255, 0
	s_addc_u32 s4, s4, 0
	s_mul_i32 s65, s65, s4
	s_add_u32 s4, s58, 0x80200
	s_addc_u32 s5, s59, 0
	s_add_u32 s6, s58, 0x80400
	s_addc_u32 s7, s59, 0
	s_add_u32 s8, s58, 0x80500
	s_addc_u32 s9, s59, 0
	s_add_u32 s10, s58, 0x80600
	s_addc_u32 s11, s59, 0
	s_add_u32 s12, s58, 0x80700
	s_addc_u32 s13, s59, 0
	s_add_u32 s16, s58, 0x80800
	s_addc_u32 s17, s59, 0
	s_add_u32 s18, s58, 0x80900
	s_addc_u32 s19, s59, 0
	s_add_u32 s22, s58, 0x80a00
	s_addc_u32 s23, s59, 0
	s_add_u32 s24, s58, 0x80b00
	s_addc_u32 s25, s59, 0
	s_add_u32 s26, s58, 0x80c00
	s_addc_u32 s27, s59, 0
	s_add_u32 s34, s58, 0x80d00
	s_addc_u32 s35, s59, 0
	s_add_u32 s36, s58, 0x80e00
	s_addc_u32 s37, s59, 0
	s_add_u32 s40, s58, 0x80f00
	s_addc_u32 s41, s59, 0
	s_add_u32 s46, s58, 0x81000
	s_addc_u32 s47, s59, 0
	s_add_u32 s48, s58, 0x81100
	s_addc_u32 s49, s59, 0
	s_add_u32 s50, s58, 0x81200
	s_addc_u32 s51, s59, 0
	s_add_u32 s52, s58, 0x81300
	s_addc_u32 s53, s59, 0
	s_branch .LBB0_3018
